# silu epilogue: dropped 74 dead s_nop pads left from the removed division sequences (hazards re-checked)
# speedup vs baseline: 1.0226x; 1.0031x over previous
; DI bf16x8 pack8(f32x8 v) { bf8v b = __builtin_convertvector(v, bf8v); return __builtin_bit_cast(bf16x8, b); }
;     __device__ __forceinline__ void operator()(const pg8::f32x4 (&acc)[2][2][4][2], const pg8::Unit& u, int wr, int wc, int fr, int fq) const {
;         const int ms = (u.pn & 7) >> 1, mixer = ((ms & 1) << 1) | (ms >> 1);
;         const int sec = u.pn >> 3, head = 4 * (u.pn & 1) + wc;
;         const int b = u.pm >> 5, blk = u.pm & 31, sbase = blk * 256 + wr * 64 + fr, bh = b * 8 + head;
;     ...
;         } else {
;             const int col = 512 * mixer + 256 * (u.pn & 1) + 64 * wc + 8 * fq;
; #pragma unroll
;             for (int ai = 0; ai < 2; ++ai)
; #pragma unroll
;                 for (int m = 0; m < 4; ++m) {
;                     const size_t row = (size_t)u.pm * 256 + 128 * ai + 64 * wr + 16 * m + fr;
; #pragma unroll
;                     for (int bj = 0; bj < 2; ++bj) {
;                         f32x8 t;
; #pragma unroll
;                         for (int n = 0; n < 2; ++n)
; #pragma unroll
;                             for (int e = 0; e < 4; ++e) { const float z = acc[ai][bj][m][n][e]; t[4 * n + e] = z / (1.0f + __expf(-z)); }
;                         *(bf16x8*)(G + row * DM + col + 32 * bj) = pack8(t);
;                     }
;                 }
;         }
.LBB0_134:
	s_bfe_u32 s1, s14, 0x10002
	s_and_b32 s2, s14, 2
	s_or_b32 s31, s1, s2
	s_and_b32 s1, s14, 1
	s_ashr_i32 s3, s0, 2
	s_lshl_b32 s2, s1, 2
	s_and_b32 s29, s0, 31
	s_and_b32 s3, s3, -8
	s_lshl_b32 s4, s29, 8
	s_or_b32 s2, s3, s2
	s_ashr_i32 s15, s14, 3
	s_add_i32 s4, s4, s58
	s_or_b32 s38, s2, s57
	v_or_b32_e32 v218, s4, v165
	s_cmp_gt_i32 s15, 1
	s_mov_b64 s[2:3], -1
	s_cbranch_scc0 .LBB0_141
	s_cmp_lg_u32 s15, 2
	s_cbranch_scc0 .LBB0_137
	v_mul_f32_e32 v2, 0xbfb8aa3b, v128
	v_exp_f32_e32 v132, v2
	v_mul_f32_e32 v2, 0xbfb8aa3b, v129
	v_exp_f32_e32 v133, v2
	s_lshl_b32 s2, s31, 9
	s_lshl_b32 s1, s1, 8
	s_or_b32 s1, s2, s1
	v_pk_add_f32 v[132:133], v[132:133], 1.0 op_sel_hi:[1,0]
	v_mul_f32_e32 v2, 0xbfb8aa3b, v130
	v_exp_f32_e32 v134, v2
	v_mul_f32_e32 v2, 0xbfb8aa3b, v131
	v_exp_f32_e32 v135, v2
	v_rcp_f32_e32 v138, v133
	s_nop 0
	v_mul_f32_e32 v138, v129, v138
	v_pk_add_f32 v[134:135], v[134:135], 1.0 op_sel_hi:[1,0]
	v_mul_f32_e32 v2, 0xbfb8aa3b, v124
	v_exp_f32_e32 v136, v2
	v_rcp_f32_e32 v133, v132
	s_nop 0
	v_mul_f32_e32 v132, v128, v133
	v_mul_f32_e32 v2, 0xbfb8aa3b, v125
	v_exp_f32_e32 v137, v2
	v_mul_f32_e32 v2, 0xbfb8aa3b, v126
	v_rcp_f32_e32 v133, v135
	s_nop 0
	v_mul_f32_e32 v133, v131, v133
	v_pk_add_f32 v[136:137], v[136:137], 1.0 op_sel_hi:[1,0]
	v_mul_f32_e32 v3, 0xbfb8aa3b, v127
	v_exp_f32_e32 v2, v2
	v_rcp_f32_e32 v135, v134
	s_nop 0
	v_mul_f32_e32 v139, v130, v135
	v_exp_f32_e32 v3, v3
	v_lshl_or_b32 v0, s57, 6, v174
	v_or_b32_e32 v0, s1, v0
	v_rcp_f32_e32 v134, v137
	s_nop 0
	v_mul_f32_e32 v134, v125, v134
	v_pk_add_f32 v[2:3], v[2:3], 1.0 op_sel_hi:[1,0]
	s_ashr_i32 s1, s0, 31
	s_lshl_b64 s[0:1], s[0:1], 20
	v_rcp_f32_e32 v135, v136
	s_nop 0
	v_mul_f32_e32 v136, v124, v135
	v_lshlrev_b32_e32 v0, 1, v0
	v_cvt_pk_bf16_f32 v134, v136, v134
	v_cvt_pk_bf16_f32 v133, v139, v133
	v_rcp_f32_e32 v135, v3
	s_nop 0
	v_mul_f32_e32 v3, v127, v135
	v_cvt_pk_bf16_f32 v132, v132, v138
	s_mov_b64 s[2:3], 0
	v_rcp_f32_e32 v135, v2
	s_nop 0
	v_mul_f32_e32 v2, v126, v135
	v_cvt_pk_bf16_f32 v135, v2, v3
	v_lshl_add_u64 v[2:3], v[212:213], 0, s[0:1]
	v_lshl_add_u64 v[2:3], v[2:3], 0, v[0:1]
	v_mul_f32_e32 v0, 0xbfb8aa3b, v120
	global_store_dwordx4 v[2:3], v[132:135], off
	s_nop 1
	v_exp_f32_e32 v134, v0
	v_mul_f32_e32 v0, 0xbfb8aa3b, v121
	v_exp_f32_e32 v135, v0
	v_mul_f32_e32 v0, 0xbfb8aa3b, v122
	v_exp_f32_e32 v136, v0
	v_mul_f32_e32 v0, 0xbfb8aa3b, v123
	v_exp_f32_e32 v137, v0
	v_mul_f32_e32 v0, 0xbfb8aa3b, v116
	v_exp_f32_e32 v138, v0
	v_mul_f32_e32 v0, 0xbfb8aa3b, v117
	v_exp_f32_e32 v139, v0
	v_mul_f32_e32 v0, 0xbfb8aa3b, v118
	v_exp_f32_e32 v132, v0
	v_mul_f32_e32 v0, 0xbfb8aa3b, v119
	v_pk_add_f32 v[134:135], v[134:135], 1.0 op_sel_hi:[1,0]
	v_exp_f32_e32 v133, v0
	v_pk_add_f32 v[136:137], v[136:137], 1.0 op_sel_hi:[1,0]
	v_pk_add_f32 v[138:139], v[138:139], 1.0 op_sel_hi:[1,0]
	v_pk_add_f32 v[132:133], v[132:133], 1.0 op_sel_hi:[1,0]
	v_rcp_f32_e32 v0, v135
	s_nop 0
	v_mul_f32_e32 v0, v121, v0
	v_rcp_f32_e32 v135, v134
	s_nop 0
	v_mul_f32_e32 v140, v120, v135
	v_rcp_f32_e32 v134, v137
	s_nop 0
	v_mul_f32_e32 v137, v123, v134
	v_rcp_f32_e32 v134, v136
	s_nop 0
	v_mul_f32_e32 v136, v122, v134
	v_rcp_f32_e32 v134, v139
	s_nop 0
	v_mul_f32_e32 v134, v117, v134
	v_rcp_f32_e32 v135, v138
	s_nop 0
	v_mul_f32_e32 v138, v116, v135
	v_cvt_pk_bf16_f32 v134, v138, v134
	v_rcp_f32_e32 v135, v133
	s_nop 0
	v_mul_f32_e32 v133, v119, v135
	v_rcp_f32_e32 v135, v132
	s_nop 0
	v_mul_f32_e32 v132, v118, v135
	v_cvt_pk_bf16_f32 v135, v132, v133
	v_cvt_pk_bf16_f32 v133, v136, v137
	v_cvt_pk_bf16_f32 v132, v140, v0
	v_mul_f32_e32 v0, 0xbfb8aa3b, v112
	global_store_dwordx4 v[2:3], v[132:135], off offset:64
	s_nop 1
	v_exp_f32_e32 v134, v0
	v_mul_f32_e32 v0, 0xbfb8aa3b, v113
	v_exp_f32_e32 v135, v0
	v_mul_f32_e32 v0, 0xbfb8aa3b, v114
	v_exp_f32_e32 v136, v0
	v_mul_f32_e32 v0, 0xbfb8aa3b, v115
	v_exp_f32_e32 v137, v0
	v_mul_f32_e32 v0, 0xbfb8aa3b, v108
	v_exp_f32_e32 v138, v0
	v_mul_f32_e32 v0, 0xbfb8aa3b, v109
	v_exp_f32_e32 v139, v0
	v_mul_f32_e32 v0, 0xbfb8aa3b, v110
	v_exp_f32_e32 v132, v0
	v_mul_f32_e32 v0, 0xbfb8aa3b, v111
	v_pk_add_f32 v[134:135], v[134:135], 1.0 op_sel_hi:[1,0]
	v_exp_f32_e32 v133, v0
	v_pk_add_f32 v[136:137], v[136:137], 1.0 op_sel_hi:[1,0]
	v_pk_add_f32 v[138:139], v[138:139], 1.0 op_sel_hi:[1,0]
	v_pk_add_f32 v[132:133], v[132:133], 1.0 op_sel_hi:[1,0]
	v_rcp_f32_e32 v0, v135
	s_nop 0
	v_mul_f32_e32 v0, v113, v0
	v_rcp_f32_e32 v135, v134
	s_nop 0
	v_mul_f32_e32 v134, v112, v135
	v_cvt_pk_bf16_f32 v134, v134, v0
	v_mul_f32_e32 v0, 0xbfb8aa3b, v104
	v_rcp_f32_e32 v135, v137
	s_nop 0
	v_mul_f32_e32 v135, v115, v135
	v_rcp_f32_e32 v137, v136
	s_nop 0
	v_mul_f32_e32 v140, v114, v137
	v_cvt_pk_bf16_f32 v135, v140, v135
	v_rcp_f32_e32 v136, v139
	s_nop 0
	v_mul_f32_e32 v136, v109, v136
	v_rcp_f32_e32 v137, v138
	s_nop 0
	v_mul_f32_e32 v138, v108, v137
	v_cvt_pk_bf16_f32 v136, v138, v136
	v_rcp_f32_e32 v137, v133
	s_nop 0
	v_mul_f32_e32 v133, v111, v137
	s_mov_b64 s[0:1], 0x10000
	v_rcp_f32_e32 v137, v132
	s_nop 0
	v_mul_f32_e32 v132, v110, v137
	v_cvt_pk_bf16_f32 v137, v132, v133
	v_lshl_add_u64 v[132:133], v[2:3], 0, s[0:1]
	s_mov_b32 s0, 0x10000
	v_add_co_u32_e32 v138, vcc, s0, v2
	v_addc_co_u32_e32 v139, vcc, 0, v3, vcc
	global_store_dwordx4 v[138:139], v[134:137], off
	s_nop 1
	v_exp_f32_e32 v136, v0
	v_mul_f32_e32 v0, 0xbfb8aa3b, v105
	v_exp_f32_e32 v137, v0
	v_mul_f32_e32 v0, 0xbfb8aa3b, v106
	v_exp_f32_e32 v138, v0
	v_mul_f32_e32 v0, 0xbfb8aa3b, v107
	v_exp_f32_e32 v139, v0
	v_mul_f32_e32 v0, 0xbfb8aa3b, v100
	v_exp_f32_e32 v140, v0
	v_mul_f32_e32 v0, 0xbfb8aa3b, v101
	v_exp_f32_e32 v141, v0
	v_mul_f32_e32 v0, 0xbfb8aa3b, v102
; DI bf16x8 pack8(f32x8 v) { bf8v b = __builtin_convertvector(v, bf8v); return __builtin_bit_cast(bf16x8, b); }
;     __device__ __forceinline__ void operator()(const pg8::f32x4 (&acc)[2][2][4][2], const pg8::Unit& u, int wr, int wc, int fr, int fq) const {
;     ...
;             for (int ai = 0; ai < 2; ++ai)
; #pragma unroll
;                 for (int m = 0; m < 4; ++m) {
;                     const size_t row = (size_t)u.pm * 256 + 128 * ai + 64 * wr + 16 * m + fr;
; #pragma unroll
;                     for (int bj = 0; bj < 2; ++bj) {
;                         f32x8 t;
; #pragma unroll
;                         for (int n = 0; n < 2; ++n)
; #pragma unroll
;                             for (int e = 0; e < 4; ++e) { const float z = acc[ai][bj][m][n][e]; t[4 * n + e] = z / (1.0f + __expf(-z)); }
;                         *(bf16x8*)(G + row * DM + col + 32 * bj) = pack8(t);
;                     }
;                 }
	v_exp_f32_e32 v134, v0
	v_mul_f32_e32 v0, 0xbfb8aa3b, v103
	v_pk_add_f32 v[136:137], v[136:137], 1.0 op_sel_hi:[1,0]
	v_exp_f32_e32 v135, v0
	v_pk_add_f32 v[138:139], v[138:139], 1.0 op_sel_hi:[1,0]
	v_pk_add_f32 v[140:141], v[140:141], 1.0 op_sel_hi:[1,0]
	v_pk_add_f32 v[134:135], v[134:135], 1.0 op_sel_hi:[1,0]
	v_rcp_f32_e32 v0, v137
	s_nop 0
	v_mul_f32_e32 v0, v105, v0
	v_rcp_f32_e32 v137, v136
	s_nop 0
	v_mul_f32_e32 v142, v104, v137
	v_rcp_f32_e32 v136, v139
	s_nop 0
	v_mul_f32_e32 v139, v107, v136
	v_rcp_f32_e32 v136, v138
	s_nop 0
	v_mul_f32_e32 v138, v106, v136
	v_rcp_f32_e32 v136, v141
	s_nop 0
	v_mul_f32_e32 v136, v101, v136
	v_rcp_f32_e32 v137, v140
	s_nop 0
	v_mul_f32_e32 v140, v100, v137
	v_cvt_pk_bf16_f32 v136, v140, v136
	v_rcp_f32_e32 v137, v135
	s_nop 0
	v_mul_f32_e32 v135, v103, v137
	v_rcp_f32_e32 v137, v134
	s_nop 0
	v_mul_f32_e32 v134, v102, v137
	v_cvt_pk_bf16_f32 v137, v134, v135
	v_cvt_pk_bf16_f32 v135, v138, v139
	v_cvt_pk_bf16_f32 v134, v142, v0
	v_mul_f32_e32 v0, 0xbfb8aa3b, v96
	global_store_dwordx4 v[132:133], v[134:137], off offset:64
	s_nop 1
	v_exp_f32_e32 v134, v0
	v_mul_f32_e32 v0, 0xbfb8aa3b, v97
	v_exp_f32_e32 v135, v0
	v_mul_f32_e32 v0, 0xbfb8aa3b, v98
	v_exp_f32_e32 v136, v0
	v_mul_f32_e32 v0, 0xbfb8aa3b, v99
	v_exp_f32_e32 v137, v0
	v_mul_f32_e32 v0, 0xbfb8aa3b, v92
	v_exp_f32_e32 v138, v0
	v_mul_f32_e32 v0, 0xbfb8aa3b, v93
	v_exp_f32_e32 v139, v0
	v_mul_f32_e32 v0, 0xbfb8aa3b, v94
	v_exp_f32_e32 v132, v0
	v_mul_f32_e32 v0, 0xbfb8aa3b, v95
	v_pk_add_f32 v[134:135], v[134:135], 1.0 op_sel_hi:[1,0]
	v_exp_f32_e32 v133, v0
	v_pk_add_f32 v[136:137], v[136:137], 1.0 op_sel_hi:[1,0]
	v_pk_add_f32 v[138:139], v[138:139], 1.0 op_sel_hi:[1,0]
	v_pk_add_f32 v[132:133], v[132:133], 1.0 op_sel_hi:[1,0]
	v_rcp_f32_e32 v0, v135
	s_nop 0
	v_mul_f32_e32 v0, v97, v0
	v_rcp_f32_e32 v135, v134
	s_nop 0
	v_mul_f32_e32 v134, v96, v135
	v_cvt_pk_bf16_f32 v134, v134, v0
	v_mul_f32_e32 v0, 0xbfb8aa3b, v88
	v_rcp_f32_e32 v135, v137
	s_nop 0
	v_mul_f32_e32 v135, v99, v135
	v_rcp_f32_e32 v137, v136
	s_nop 0
	v_mul_f32_e32 v140, v98, v137
	v_cvt_pk_bf16_f32 v135, v140, v135
	v_rcp_f32_e32 v136, v139
	s_nop 0
	v_mul_f32_e32 v136, v93, v136
	v_rcp_f32_e32 v137, v138
	s_nop 0
	v_mul_f32_e32 v138, v92, v137
	v_cvt_pk_bf16_f32 v136, v138, v136
	v_rcp_f32_e32 v137, v133
	s_nop 0
	v_mul_f32_e32 v133, v95, v137
	s_mov_b32 s0, 0x20000
	v_rcp_f32_e32 v137, v132
	s_nop 0
	v_mul_f32_e32 v132, v94, v137
	v_add_co_u32_e32 v138, vcc, s0, v2
	v_cvt_pk_bf16_f32 v137, v132, v133
	s_nop 0
	v_addc_co_u32_e32 v139, vcc, 0, v3, vcc
	global_store_dwordx4 v[138:139], v[134:137], off
	v_lshl_add_u64 v[132:133], v[2:3], 0, s[72:73]
	v_exp_f32_e32 v136, v0
	v_mul_f32_e32 v0, 0xbfb8aa3b, v89
	v_exp_f32_e32 v137, v0
	v_mul_f32_e32 v0, 0xbfb8aa3b, v90
	v_exp_f32_e32 v138, v0
	v_mul_f32_e32 v0, 0xbfb8aa3b, v91
	v_exp_f32_e32 v139, v0
	v_mul_f32_e32 v0, 0xbfb8aa3b, v84
	v_exp_f32_e32 v140, v0
	v_mul_f32_e32 v0, 0xbfb8aa3b, v85
	v_exp_f32_e32 v141, v0
	v_mul_f32_e32 v0, 0xbfb8aa3b, v86
	v_exp_f32_e32 v134, v0
	v_mul_f32_e32 v0, 0xbfb8aa3b, v87
	v_pk_add_f32 v[136:137], v[136:137], 1.0 op_sel_hi:[1,0]
	v_exp_f32_e32 v135, v0
	v_pk_add_f32 v[138:139], v[138:139], 1.0 op_sel_hi:[1,0]
	v_pk_add_f32 v[140:141], v[140:141], 1.0 op_sel_hi:[1,0]
	v_pk_add_f32 v[134:135], v[134:135], 1.0 op_sel_hi:[1,0]
	v_rcp_f32_e32 v0, v137
	s_nop 0
	v_mul_f32_e32 v0, v89, v0
	v_rcp_f32_e32 v137, v136
	s_nop 0
	v_mul_f32_e32 v142, v88, v137
	v_rcp_f32_e32 v136, v139
	s_nop 0
	v_mul_f32_e32 v139, v91, v136
	v_rcp_f32_e32 v136, v138
	s_nop 0
	v_mul_f32_e32 v138, v90, v136
	v_rcp_f32_e32 v136, v141
	s_nop 0
	v_mul_f32_e32 v136, v85, v136
	v_rcp_f32_e32 v137, v140
	s_nop 0
	v_mul_f32_e32 v140, v84, v137
	v_cvt_pk_bf16_f32 v136, v140, v136
	v_rcp_f32_e32 v137, v135
	s_nop 0
	v_mul_f32_e32 v135, v87, v137
	v_rcp_f32_e32 v137, v134
	s_nop 0
	v_mul_f32_e32 v134, v86, v137
	v_cvt_pk_bf16_f32 v137, v134, v135
	v_cvt_pk_bf16_f32 v135, v138, v139
	v_cvt_pk_bf16_f32 v134, v142, v0
	v_mul_f32_e32 v0, 0xbfb8aa3b, v80
	global_store_dwordx4 v[132:133], v[134:137], off offset:64
	s_nop 1
	v_exp_f32_e32 v134, v0
	v_mul_f32_e32 v0, 0xbfb8aa3b, v81
	v_exp_f32_e32 v135, v0
	v_mul_f32_e32 v0, 0xbfb8aa3b, v82
	v_exp_f32_e32 v136, v0
	v_mul_f32_e32 v0, 0xbfb8aa3b, v83
	v_exp_f32_e32 v137, v0
	v_mul_f32_e32 v0, 0xbfb8aa3b, v76
	v_exp_f32_e32 v138, v0
	v_mul_f32_e32 v0, 0xbfb8aa3b, v77
	v_exp_f32_e32 v139, v0
	v_mul_f32_e32 v0, 0xbfb8aa3b, v78
	v_exp_f32_e32 v132, v0
	v_mul_f32_e32 v0, 0xbfb8aa3b, v79
	v_pk_add_f32 v[134:135], v[134:135], 1.0 op_sel_hi:[1,0]
	v_exp_f32_e32 v133, v0
	v_pk_add_f32 v[136:137], v[136:137], 1.0 op_sel_hi:[1,0]
	v_pk_add_f32 v[138:139], v[138:139], 1.0 op_sel_hi:[1,0]
	v_pk_add_f32 v[132:133], v[132:133], 1.0 op_sel_hi:[1,0]
	v_rcp_f32_e32 v0, v135
	s_nop 0
	v_mul_f32_e32 v0, v81, v0
	v_rcp_f32_e32 v135, v134
	s_nop 0
	v_mul_f32_e32 v134, v80, v135
	v_cvt_pk_bf16_f32 v134, v134, v0
	v_mul_f32_e32 v0, 0xbfb8aa3b, v72
	v_rcp_f32_e32 v135, v137
	s_nop 0
	v_mul_f32_e32 v135, v83, v135
	v_rcp_f32_e32 v137, v136
	s_nop 0
	v_mul_f32_e32 v140, v82, v137
	v_cvt_pk_bf16_f32 v135, v140, v135
	v_rcp_f32_e32 v136, v139
	s_nop 0
	v_mul_f32_e32 v136, v77, v136
	v_rcp_f32_e32 v137, v138
	s_nop 0
	v_mul_f32_e32 v138, v76, v137
	v_cvt_pk_bf16_f32 v136, v138, v136
	v_rcp_f32_e32 v137, v133
	s_nop 0
	v_mul_f32_e32 v133, v79, v137
	s_mov_b64 s[0:1], 0x30000
	v_rcp_f32_e32 v137, v132
	s_nop 0
	v_mul_f32_e32 v132, v78, v137
	v_cvt_pk_bf16_f32 v137, v132, v133
	v_lshl_add_u64 v[132:133], v[2:3], 0, s[0:1]
	s_mov_b32 s0, 0x30000
	v_add_co_u32_e32 v138, vcc, s0, v2
	v_addc_co_u32_e32 v139, vcc, 0, v3, vcc
; DI bf16x8 pack8(f32x8 v) { bf8v b = __builtin_convertvector(v, bf8v); return __builtin_bit_cast(bf16x8, b); }
;     __device__ __forceinline__ void operator()(const pg8::f32x4 (&acc)[2][2][4][2], const pg8::Unit& u, int wr, int wc, int fr, int fq) const {
;     ...
;             for (int ai = 0; ai < 2; ++ai)
; #pragma unroll
;                 for (int m = 0; m < 4; ++m) {
;                     const size_t row = (size_t)u.pm * 256 + 128 * ai + 64 * wr + 16 * m + fr;
; #pragma unroll
;                     for (int bj = 0; bj < 2; ++bj) {
;                         f32x8 t;
; #pragma unroll
;                         for (int n = 0; n < 2; ++n)
; #pragma unroll
;                             for (int e = 0; e < 4; ++e) { const float z = acc[ai][bj][m][n][e]; t[4 * n + e] = z / (1.0f + __expf(-z)); }
;                         *(bf16x8*)(G + row * DM + col + 32 * bj) = pack8(t);
;                     }
;                 }
	global_store_dwordx4 v[138:139], v[134:137], off
	s_nop 1
	v_exp_f32_e32 v136, v0
	v_mul_f32_e32 v0, 0xbfb8aa3b, v73
	v_exp_f32_e32 v137, v0
	v_mul_f32_e32 v0, 0xbfb8aa3b, v74
	v_exp_f32_e32 v138, v0
	v_mul_f32_e32 v0, 0xbfb8aa3b, v75
	v_exp_f32_e32 v139, v0
	v_mul_f32_e32 v0, 0xbfb8aa3b, v68
	v_exp_f32_e32 v140, v0
	v_mul_f32_e32 v0, 0xbfb8aa3b, v69
	v_exp_f32_e32 v141, v0
	v_mul_f32_e32 v0, 0xbfb8aa3b, v70
	v_exp_f32_e32 v134, v0
	v_mul_f32_e32 v0, 0xbfb8aa3b, v71
	v_pk_add_f32 v[136:137], v[136:137], 1.0 op_sel_hi:[1,0]
	v_exp_f32_e32 v135, v0
	v_pk_add_f32 v[138:139], v[138:139], 1.0 op_sel_hi:[1,0]
	v_pk_add_f32 v[140:141], v[140:141], 1.0 op_sel_hi:[1,0]
	v_pk_add_f32 v[134:135], v[134:135], 1.0 op_sel_hi:[1,0]
	v_rcp_f32_e32 v0, v137
	s_nop 0
	v_mul_f32_e32 v0, v73, v0
	v_rcp_f32_e32 v137, v136
	s_nop 0
	v_mul_f32_e32 v142, v72, v137
	v_rcp_f32_e32 v136, v139
	s_nop 0
	v_mul_f32_e32 v139, v75, v136
	v_rcp_f32_e32 v136, v138
	s_nop 0
	v_mul_f32_e32 v138, v74, v136
	v_rcp_f32_e32 v136, v141
	s_nop 0
	v_mul_f32_e32 v136, v69, v136
	v_rcp_f32_e32 v137, v140
	s_nop 0
	v_mul_f32_e32 v140, v68, v137
	v_cvt_pk_bf16_f32 v136, v140, v136
	v_rcp_f32_e32 v137, v135
	s_nop 0
	v_mul_f32_e32 v135, v71, v137
	v_rcp_f32_e32 v137, v134
	s_nop 0
	v_mul_f32_e32 v134, v70, v137
	v_cvt_pk_bf16_f32 v137, v134, v135
	v_cvt_pk_bf16_f32 v135, v138, v139
	v_cvt_pk_bf16_f32 v134, v142, v0
	v_mul_f32_e32 v0, 0xbfb8aa3b, v64
	global_store_dwordx4 v[132:133], v[134:137], off offset:64
	s_nop 1
	v_exp_f32_e32 v134, v0
	v_mul_f32_e32 v0, 0xbfb8aa3b, v65
	v_exp_f32_e32 v135, v0
	v_mul_f32_e32 v0, 0xbfb8aa3b, v66
	v_exp_f32_e32 v136, v0
	v_mul_f32_e32 v0, 0xbfb8aa3b, v67
	v_exp_f32_e32 v137, v0
	v_mul_f32_e32 v0, 0xbfb8aa3b, v60
	v_exp_f32_e32 v138, v0
	v_mul_f32_e32 v0, 0xbfb8aa3b, v61
	v_exp_f32_e32 v139, v0
	v_mul_f32_e32 v0, 0xbfb8aa3b, v62
	v_exp_f32_e32 v132, v0
	v_mul_f32_e32 v0, 0xbfb8aa3b, v63
	v_pk_add_f32 v[134:135], v[134:135], 1.0 op_sel_hi:[1,0]
	v_exp_f32_e32 v133, v0
	v_pk_add_f32 v[136:137], v[136:137], 1.0 op_sel_hi:[1,0]
	v_pk_add_f32 v[138:139], v[138:139], 1.0 op_sel_hi:[1,0]
	v_pk_add_f32 v[132:133], v[132:133], 1.0 op_sel_hi:[1,0]
	v_rcp_f32_e32 v0, v135
	s_nop 0
	v_mul_f32_e32 v0, v65, v0
	v_rcp_f32_e32 v135, v134
	s_nop 0
	v_mul_f32_e32 v134, v64, v135
	v_cvt_pk_bf16_f32 v134, v134, v0
	v_mul_f32_e32 v0, 0xbfb8aa3b, v56
	v_rcp_f32_e32 v135, v137
	s_nop 0
	v_mul_f32_e32 v135, v67, v135
	v_rcp_f32_e32 v137, v136
	s_nop 0
	v_mul_f32_e32 v140, v66, v137
	v_cvt_pk_bf16_f32 v135, v140, v135
	v_rcp_f32_e32 v136, v139
	s_nop 0
	v_mul_f32_e32 v136, v61, v136
	v_rcp_f32_e32 v137, v138
	s_nop 0
	v_mul_f32_e32 v138, v60, v137
	v_cvt_pk_bf16_f32 v136, v138, v136
	v_rcp_f32_e32 v137, v133
	s_nop 0
	v_mul_f32_e32 v133, v63, v137
	s_mov_b64 s[0:1], 0x80000
	v_rcp_f32_e32 v137, v132
	s_nop 0
	v_mul_f32_e32 v132, v62, v137
	v_add_co_u32_e32 v138, vcc, s33, v2
	v_cvt_pk_bf16_f32 v137, v132, v133
	s_nop 0
	v_addc_co_u32_e32 v139, vcc, 0, v3, vcc
	global_store_dwordx4 v[138:139], v[134:137], off
	v_lshl_add_u64 v[132:133], v[2:3], 0, s[0:1]
	v_exp_f32_e32 v136, v0
	v_mul_f32_e32 v0, 0xbfb8aa3b, v57
	v_exp_f32_e32 v137, v0
	v_mul_f32_e32 v0, 0xbfb8aa3b, v58
	v_exp_f32_e32 v138, v0
	v_mul_f32_e32 v0, 0xbfb8aa3b, v59
	v_exp_f32_e32 v139, v0
	v_mul_f32_e32 v0, 0xbfb8aa3b, v52
	v_exp_f32_e32 v140, v0
	v_mul_f32_e32 v0, 0xbfb8aa3b, v53
	v_exp_f32_e32 v141, v0
	v_mul_f32_e32 v0, 0xbfb8aa3b, v54
	v_exp_f32_e32 v134, v0
	v_mul_f32_e32 v0, 0xbfb8aa3b, v55
	v_pk_add_f32 v[136:137], v[136:137], 1.0 op_sel_hi:[1,0]
	v_exp_f32_e32 v135, v0
	v_pk_add_f32 v[138:139], v[138:139], 1.0 op_sel_hi:[1,0]
	v_pk_add_f32 v[140:141], v[140:141], 1.0 op_sel_hi:[1,0]
	v_pk_add_f32 v[134:135], v[134:135], 1.0 op_sel_hi:[1,0]
	v_rcp_f32_e32 v0, v137
	s_nop 0
	v_mul_f32_e32 v0, v57, v0
	v_rcp_f32_e32 v137, v136
	s_nop 0
	v_mul_f32_e32 v142, v56, v137
	v_rcp_f32_e32 v136, v139
	s_nop 0
	v_mul_f32_e32 v139, v59, v136
	v_rcp_f32_e32 v136, v138
	s_nop 0
	v_mul_f32_e32 v138, v58, v136
	v_rcp_f32_e32 v136, v141
	s_nop 0
	v_mul_f32_e32 v136, v53, v136
	v_rcp_f32_e32 v137, v140
	s_nop 0
	v_mul_f32_e32 v140, v52, v137
	v_cvt_pk_bf16_f32 v136, v140, v136
	v_rcp_f32_e32 v137, v135
	s_nop 0
	v_mul_f32_e32 v135, v55, v137
	v_rcp_f32_e32 v137, v134
	s_nop 0
	v_mul_f32_e32 v134, v54, v137
	v_cvt_pk_bf16_f32 v137, v134, v135
	v_cvt_pk_bf16_f32 v135, v138, v139
	v_cvt_pk_bf16_f32 v134, v142, v0
	v_mul_f32_e32 v0, 0xbfb8aa3b, v48
	global_store_dwordx4 v[132:133], v[134:137], off offset:64
	s_nop 1
	v_exp_f32_e32 v134, v0
	v_mul_f32_e32 v0, 0xbfb8aa3b, v49
	v_exp_f32_e32 v135, v0
	v_mul_f32_e32 v0, 0xbfb8aa3b, v50
	v_exp_f32_e32 v136, v0
	v_mul_f32_e32 v0, 0xbfb8aa3b, v51
	v_exp_f32_e32 v137, v0
	v_mul_f32_e32 v0, 0xbfb8aa3b, v44
	v_exp_f32_e32 v138, v0
	v_mul_f32_e32 v0, 0xbfb8aa3b, v45
	v_exp_f32_e32 v139, v0
	v_mul_f32_e32 v0, 0xbfb8aa3b, v46
	v_exp_f32_e32 v132, v0
	v_mul_f32_e32 v0, 0xbfb8aa3b, v47
	v_pk_add_f32 v[134:135], v[134:135], 1.0 op_sel_hi:[1,0]
	v_exp_f32_e32 v133, v0
	v_pk_add_f32 v[136:137], v[136:137], 1.0 op_sel_hi:[1,0]
	v_pk_add_f32 v[138:139], v[138:139], 1.0 op_sel_hi:[1,0]
	v_pk_add_f32 v[132:133], v[132:133], 1.0 op_sel_hi:[1,0]
	v_rcp_f32_e32 v0, v135
	s_nop 0
	v_mul_f32_e32 v0, v49, v0
	v_rcp_f32_e32 v135, v134
	s_nop 0
	v_mul_f32_e32 v134, v48, v135
	v_cvt_pk_bf16_f32 v134, v134, v0
	v_mul_f32_e32 v0, 0xbfb8aa3b, v40
	v_rcp_f32_e32 v135, v137
	s_nop 0
	v_mul_f32_e32 v135, v51, v135
	v_rcp_f32_e32 v137, v136
	s_nop 0
	v_mul_f32_e32 v140, v50, v137
	v_cvt_pk_bf16_f32 v135, v140, v135
	v_rcp_f32_e32 v136, v139
	s_nop 0
	v_mul_f32_e32 v136, v45, v136
	v_rcp_f32_e32 v137, v138
	s_nop 0
; DI bf16x8 pack8(f32x8 v) { bf8v b = __builtin_convertvector(v, bf8v); return __builtin_bit_cast(bf16x8, b); }
;     __device__ __forceinline__ void operator()(const pg8::f32x4 (&acc)[2][2][4][2], const pg8::Unit& u, int wr, int wc, int fr, int fq) const {
;     ...
;             for (int ai = 0; ai < 2; ++ai)
; #pragma unroll
;                 for (int m = 0; m < 4; ++m) {
;                     const size_t row = (size_t)u.pm * 256 + 128 * ai + 64 * wr + 16 * m + fr;
; #pragma unroll
;                     for (int bj = 0; bj < 2; ++bj) {
;                         f32x8 t;
; #pragma unroll
;                         for (int n = 0; n < 2; ++n)
; #pragma unroll
;                             for (int e = 0; e < 4; ++e) { const float z = acc[ai][bj][m][n][e]; t[4 * n + e] = z / (1.0f + __expf(-z)); }
;                         *(bf16x8*)(G + row * DM + col + 32 * bj) = pack8(t);
;                     }
;                 }
	v_mul_f32_e32 v138, v44, v137
	v_cvt_pk_bf16_f32 v136, v138, v136
	v_rcp_f32_e32 v137, v133
	s_nop 0
	v_mul_f32_e32 v133, v47, v137
	s_mov_b64 s[0:1], 0x90000
	v_rcp_f32_e32 v137, v132
	s_nop 0
	v_mul_f32_e32 v132, v46, v137
	v_cvt_pk_bf16_f32 v137, v132, v133
	v_lshl_add_u64 v[132:133], v[2:3], 0, s[0:1]
	s_mov_b32 s0, 0x90000
	v_add_co_u32_e32 v138, vcc, s0, v2
	v_addc_co_u32_e32 v139, vcc, 0, v3, vcc
	global_store_dwordx4 v[138:139], v[134:137], off
	s_nop 1
	v_exp_f32_e32 v136, v0
	v_mul_f32_e32 v0, 0xbfb8aa3b, v41
	v_exp_f32_e32 v137, v0
	v_mul_f32_e32 v0, 0xbfb8aa3b, v42
	v_exp_f32_e32 v138, v0
	v_mul_f32_e32 v0, 0xbfb8aa3b, v43
	v_exp_f32_e32 v139, v0
	v_mul_f32_e32 v0, 0xbfb8aa3b, v36
	v_exp_f32_e32 v140, v0
	v_mul_f32_e32 v0, 0xbfb8aa3b, v37
	v_exp_f32_e32 v141, v0
	v_mul_f32_e32 v0, 0xbfb8aa3b, v38
	v_exp_f32_e32 v134, v0
	v_mul_f32_e32 v0, 0xbfb8aa3b, v39
	v_pk_add_f32 v[136:137], v[136:137], 1.0 op_sel_hi:[1,0]
	v_exp_f32_e32 v135, v0
	v_pk_add_f32 v[138:139], v[138:139], 1.0 op_sel_hi:[1,0]
	v_pk_add_f32 v[140:141], v[140:141], 1.0 op_sel_hi:[1,0]
	v_pk_add_f32 v[134:135], v[134:135], 1.0 op_sel_hi:[1,0]
	v_rcp_f32_e32 v0, v137
	s_nop 0
	v_mul_f32_e32 v0, v41, v0
	v_rcp_f32_e32 v137, v136
	s_nop 0
	v_mul_f32_e32 v142, v40, v137
	v_rcp_f32_e32 v136, v139
	s_nop 0
	v_mul_f32_e32 v139, v43, v136
	v_rcp_f32_e32 v136, v138
	s_nop 0
	v_mul_f32_e32 v138, v42, v136
	v_rcp_f32_e32 v136, v141
	s_nop 0
	v_mul_f32_e32 v136, v37, v136
	v_rcp_f32_e32 v137, v140
	s_nop 0
	v_mul_f32_e32 v140, v36, v137
	v_cvt_pk_bf16_f32 v136, v140, v136
	v_rcp_f32_e32 v137, v135
	s_nop 0
	v_mul_f32_e32 v135, v39, v137
	v_rcp_f32_e32 v137, v134
	s_nop 0
	v_mul_f32_e32 v134, v38, v137
	v_cvt_pk_bf16_f32 v137, v134, v135
	v_cvt_pk_bf16_f32 v135, v138, v139
	v_cvt_pk_bf16_f32 v134, v142, v0
	v_mul_f32_e32 v0, 0xbfb8aa3b, v32
	global_store_dwordx4 v[132:133], v[134:137], off offset:64
	s_nop 1
	v_exp_f32_e32 v134, v0
	v_mul_f32_e32 v0, 0xbfb8aa3b, v33
	v_exp_f32_e32 v135, v0
	v_mul_f32_e32 v0, 0xbfb8aa3b, v34
	v_exp_f32_e32 v136, v0
	v_mul_f32_e32 v0, 0xbfb8aa3b, v35
	v_exp_f32_e32 v137, v0
	v_mul_f32_e32 v0, 0xbfb8aa3b, v28
	v_exp_f32_e32 v138, v0
	v_mul_f32_e32 v0, 0xbfb8aa3b, v29
	v_exp_f32_e32 v139, v0
	v_mul_f32_e32 v0, 0xbfb8aa3b, v30
	v_exp_f32_e32 v132, v0
	v_mul_f32_e32 v0, 0xbfb8aa3b, v31
	v_pk_add_f32 v[134:135], v[134:135], 1.0 op_sel_hi:[1,0]
	v_exp_f32_e32 v133, v0
	v_pk_add_f32 v[136:137], v[136:137], 1.0 op_sel_hi:[1,0]
	v_pk_add_f32 v[138:139], v[138:139], 1.0 op_sel_hi:[1,0]
	v_pk_add_f32 v[132:133], v[132:133], 1.0 op_sel_hi:[1,0]
	v_rcp_f32_e32 v0, v135
	s_nop 0
	v_mul_f32_e32 v0, v33, v0
	v_rcp_f32_e32 v135, v134
	s_nop 0
	v_mul_f32_e32 v134, v32, v135
	v_cvt_pk_bf16_f32 v134, v134, v0
	v_mul_f32_e32 v0, 0xbfb8aa3b, v24
	v_rcp_f32_e32 v135, v137
	s_nop 0
	v_mul_f32_e32 v135, v35, v135
	v_rcp_f32_e32 v137, v136
	s_nop 0
	v_mul_f32_e32 v140, v34, v137
	v_cvt_pk_bf16_f32 v135, v140, v135
	v_rcp_f32_e32 v136, v139
	s_nop 0
	v_mul_f32_e32 v136, v29, v136
	v_rcp_f32_e32 v137, v138
	s_nop 0
	v_mul_f32_e32 v138, v28, v137
	v_cvt_pk_bf16_f32 v136, v138, v136
	v_rcp_f32_e32 v137, v133
	s_nop 0
	v_mul_f32_e32 v133, v31, v137
	s_mov_b64 s[0:1], 0xa0000
	v_rcp_f32_e32 v137, v132
	s_nop 0
	v_mul_f32_e32 v132, v30, v137
	v_cvt_pk_bf16_f32 v137, v132, v133
	v_lshl_add_u64 v[132:133], v[2:3], 0, s[0:1]
	s_mov_b32 s0, 0xa0000
	v_add_co_u32_e32 v138, vcc, s0, v2
	v_addc_co_u32_e32 v139, vcc, 0, v3, vcc
	global_store_dwordx4 v[138:139], v[134:137], off
	s_nop 1
	v_exp_f32_e32 v136, v0
	v_mul_f32_e32 v0, 0xbfb8aa3b, v25
	v_exp_f32_e32 v137, v0
	v_mul_f32_e32 v0, 0xbfb8aa3b, v26
	v_exp_f32_e32 v138, v0
	v_mul_f32_e32 v0, 0xbfb8aa3b, v27
	v_exp_f32_e32 v139, v0
	v_mul_f32_e32 v0, 0xbfb8aa3b, v20
	v_exp_f32_e32 v140, v0
	v_mul_f32_e32 v0, 0xbfb8aa3b, v21
	v_exp_f32_e32 v141, v0
	v_mul_f32_e32 v0, 0xbfb8aa3b, v22
	v_exp_f32_e32 v134, v0
	v_mul_f32_e32 v0, 0xbfb8aa3b, v23
; DI bf16x8 pack8(f32x8 v) { bf8v b = __builtin_convertvector(v, bf8v); return __builtin_bit_cast(bf16x8, b); }
;     __device__ __forceinline__ void operator()(const pg8::f32x4 (&acc)[2][2][4][2], const pg8::Unit& u, int wr, int wc, int fr, int fq) const {
;     ...
;             for (int ai = 0; ai < 2; ++ai)
; #pragma unroll
;                 for (int m = 0; m < 4; ++m) {
;                     const size_t row = (size_t)u.pm * 256 + 128 * ai + 64 * wr + 16 * m + fr;
; #pragma unroll
;                     for (int bj = 0; bj < 2; ++bj) {
;                         f32x8 t;
; #pragma unroll
;                         for (int n = 0; n < 2; ++n)
; #pragma unroll
;                             for (int e = 0; e < 4; ++e) { const float z = acc[ai][bj][m][n][e]; t[4 * n + e] = z / (1.0f + __expf(-z)); }
;                         *(bf16x8*)(G + row * DM + col + 32 * bj) = pack8(t);
;                     }
;                 }
	v_pk_add_f32 v[136:137], v[136:137], 1.0 op_sel_hi:[1,0]
	v_exp_f32_e32 v135, v0
	v_pk_add_f32 v[138:139], v[138:139], 1.0 op_sel_hi:[1,0]
	v_pk_add_f32 v[140:141], v[140:141], 1.0 op_sel_hi:[1,0]
	v_pk_add_f32 v[134:135], v[134:135], 1.0 op_sel_hi:[1,0]
	v_rcp_f32_e32 v0, v137
	s_nop 0
	v_mul_f32_e32 v0, v25, v0
	v_rcp_f32_e32 v137, v136
	s_nop 0
	v_mul_f32_e32 v142, v24, v137
	v_rcp_f32_e32 v136, v139
	s_nop 0
	v_mul_f32_e32 v139, v27, v136
	v_rcp_f32_e32 v136, v138
	s_nop 0
	v_mul_f32_e32 v138, v26, v136
	v_rcp_f32_e32 v136, v141
	s_nop 0
	v_mul_f32_e32 v136, v21, v136
	v_rcp_f32_e32 v137, v140
	s_nop 0
	v_mul_f32_e32 v140, v20, v137
	v_cvt_pk_bf16_f32 v136, v140, v136
	v_rcp_f32_e32 v137, v135
	s_nop 0
	v_mul_f32_e32 v135, v23, v137
	v_rcp_f32_e32 v137, v134
	s_nop 0
	v_mul_f32_e32 v134, v22, v137
	v_cvt_pk_bf16_f32 v137, v134, v135
	v_cvt_pk_bf16_f32 v135, v138, v139
	v_cvt_pk_bf16_f32 v134, v142, v0
	v_mul_f32_e32 v0, 0xbfb8aa3b, v16
	global_store_dwordx4 v[132:133], v[134:137], off offset:64
	s_nop 1
	v_exp_f32_e32 v134, v0
	v_mul_f32_e32 v0, 0xbfb8aa3b, v17
	v_exp_f32_e32 v135, v0
	v_mul_f32_e32 v0, 0xbfb8aa3b, v18
	v_exp_f32_e32 v136, v0
	v_mul_f32_e32 v0, 0xbfb8aa3b, v19
	v_exp_f32_e32 v137, v0
	v_mul_f32_e32 v0, 0xbfb8aa3b, v12
	v_exp_f32_e32 v138, v0
	v_mul_f32_e32 v0, 0xbfb8aa3b, v13
	v_exp_f32_e32 v139, v0
	v_mul_f32_e32 v0, 0xbfb8aa3b, v14
	v_exp_f32_e32 v132, v0
	v_mul_f32_e32 v0, 0xbfb8aa3b, v15
	v_pk_add_f32 v[134:135], v[134:135], 1.0 op_sel_hi:[1,0]
	v_exp_f32_e32 v133, v0
	v_pk_add_f32 v[136:137], v[136:137], 1.0 op_sel_hi:[1,0]
	v_pk_add_f32 v[138:139], v[138:139], 1.0 op_sel_hi:[1,0]
	v_pk_add_f32 v[132:133], v[132:133], 1.0 op_sel_hi:[1,0]
	v_rcp_f32_e32 v0, v135
	s_nop 0
	v_mul_f32_e32 v0, v17, v0
	v_rcp_f32_e32 v135, v134
	s_nop 0
	v_mul_f32_e32 v134, v16, v135
	v_cvt_pk_bf16_f32 v134, v134, v0
	v_mul_f32_e32 v0, 0xbfb8aa3b, v8
	v_rcp_f32_e32 v135, v137
	s_nop 0
	v_mul_f32_e32 v135, v19, v135
	v_rcp_f32_e32 v137, v136
	s_nop 0
	v_mul_f32_e32 v140, v18, v137
	v_cvt_pk_bf16_f32 v135, v140, v135
	v_rcp_f32_e32 v136, v139
	s_nop 0
	v_mul_f32_e32 v136, v13, v136
	v_rcp_f32_e32 v137, v138
	s_nop 0
	v_mul_f32_e32 v138, v12, v137
	v_cvt_pk_bf16_f32 v136, v138, v136
	v_rcp_f32_e32 v137, v133
	s_nop 0
	v_mul_f32_e32 v133, v15, v137
	s_mov_b64 s[0:1], 0xb0000
	v_rcp_f32_e32 v137, v132
	s_nop 0
	v_mul_f32_e32 v132, v14, v137
	v_cvt_pk_bf16_f32 v137, v132, v133
	v_lshl_add_u64 v[132:133], v[2:3], 0, s[0:1]
	s_mov_b32 s0, 0xb0000
	v_add_co_u32_e32 v2, vcc, s0, v2
	v_addc_co_u32_e32 v3, vcc, 0, v3, vcc
	global_store_dwordx4 v[2:3], v[134:137], off
	s_nop 1
	v_exp_f32_e32 v134, v0
	v_mul_f32_e32 v0, 0xbfb8aa3b, v9
	v_exp_f32_e32 v135, v0
	v_mul_f32_e32 v0, 0xbfb8aa3b, v10
	v_exp_f32_e32 v136, v0
	v_mul_f32_e32 v0, 0xbfb8aa3b, v11
	v_exp_f32_e32 v137, v0
	v_mul_f32_e32 v0, 0xbfb8aa3b, v4
	v_exp_f32_e32 v138, v0
	v_mul_f32_e32 v0, 0xbfb8aa3b, v5
	v_exp_f32_e32 v139, v0
	v_mul_f32_e32 v0, 0xbfb8aa3b, v6
	v_exp_f32_e32 v2, v0
	v_mul_f32_e32 v0, 0xbfb8aa3b, v7
	v_pk_add_f32 v[134:135], v[134:135], 1.0 op_sel_hi:[1,0]
	v_exp_f32_e32 v3, v0
	v_pk_add_f32 v[136:137], v[136:137], 1.0 op_sel_hi:[1,0]
	v_pk_add_f32 v[138:139], v[138:139], 1.0 op_sel_hi:[1,0]
	v_pk_add_f32 v[2:3], v[2:3], 1.0 op_sel_hi:[1,0]
	v_rcp_f32_e32 v0, v135
	s_nop 0
	v_mul_f32_e32 v0, v9, v0
	v_rcp_f32_e32 v135, v134
	s_nop 0
	v_mul_f32_e32 v134, v8, v135
	v_cvt_pk_bf16_f32 v134, v134, v0
	v_rcp_f32_e32 v135, v137
	s_nop 0
	v_mul_f32_e32 v135, v11, v135
	v_rcp_f32_e32 v137, v136
	s_nop 0
	v_mul_f32_e32 v140, v10, v137
	v_cvt_pk_bf16_f32 v135, v140, v135
	v_rcp_f32_e32 v136, v139
	s_nop 0
	v_mul_f32_e32 v136, v5, v136
	v_rcp_f32_e32 v137, v138
	s_nop 0
	v_mul_f32_e32 v138, v4, v137
	v_cvt_pk_bf16_f32 v136, v138, v136
	v_rcp_f32_e32 v137, v3
	s_nop 0
	v_mul_f32_e32 v3, v7, v137
	v_rcp_f32_e32 v137, v2
	s_nop 0
	v_mul_f32_e32 v2, v6, v137
	v_cvt_pk_bf16_f32 v137, v2, v3
	global_store_dwordx4 v[132:133], v[134:137], off offset:64
